# l0 retention output: the four gate-row loads issued together (was one memory round trip per 16-token tile, each behind the previous tile's store)
# speedup vs baseline: 1.0193x; 1.0051x over previous
.LBB0_1097:
	s_or_b64 exec, exec, s[34:35]
	s_waitcnt lgkmcnt(0)
	s_barrier
	ds_read_b64 v[10:11], v23 offset:280
	v_or_b32_e32 v84, s73, v1
	v_ashrrev_i32_e32 v85, 31, v84
	s_lshl_b32 s42, s36, 2
	s_mov_b32 s67, s43
	s_waitcnt lgkmcnt(0)
	v_readfirstlane_b32 s34, v10
	v_readfirstlane_b32 s35, v11
	v_lshlrev_b64 v[10:11], 13, v[84:85]
	s_add_u32 s37, s34, s42
	v_lshl_add_u64 v[10:11], s[44:45], 0, v[10:11]
	s_addc_u32 s64, s35, 0
	s_lshl_b32 s66, s51, 2
	v_lshl_add_u64 v[10:11], v[10:11], 0, s[42:43]
	v_lshlrev_b32_e32 v30, 2, v98
	v_mov_b32_e32 v31, v23
	v_lshl_add_u64 v[10:11], v[10:11], 0, s[66:67]
	v_lshl_add_u64 v[10:11], v[10:11], 0, v[30:31]
	v_add_co_u32_e64 v10, s[34:35], s72, v10
	v_mov_b64_e32 v[32:33], s[54:55]
	s_nop 0
	v_addc_co_u32_e64 v11, s[34:35], 0, v11, s[34:35]
	global_load_dwordx4 v[80:83], v[10:11], off offset:1664
	s_mov_b64 s[98:99], 0x20000
	v_lshl_add_u64 v[200:201], v[10:11], 0, s[98:99]
	v_lshl_add_u64 v[202:203], v[200:201], 0, s[98:99]
	v_lshl_add_u64 v[204:205], v[202:203], 0, s[98:99]
	global_load_dwordx4 v[208:211], v[200:201], off offset:1664
	global_load_dwordx4 v[212:215], v[202:203], off offset:1664
	global_load_dwordx4 v[216:219], v[204:205], off offset:1664
	s_add_u32 s34, s37, s66
	s_addc_u32 s35, s64, 0
	v_or_b32_e32 v104, s73, v66
	s_nop 0
	global_load_dwordx4 v[10:13], v30, s[34:35]
	ds_read2st64_b32 v[86:87], v65 offset1:1
	ds_read2st64_b32 v[88:89], v65 offset0:2 offset1:3
	ds_read2st64_b32 v[90:91], v65 offset0:4 offset1:5
	ds_read2st64_b32 v[92:93], v65 offset0:6 offset1:7
	ds_read2st64_b32 v[94:95], v67 offset1:1
	ds_read2st64_b32 v[96:97], v67 offset0:2 offset1:3
	ds_read2st64_b32 v[100:101], v67 offset0:4 offset1:5
	ds_read2st64_b32 v[102:103], v67 offset0:6 offset1:7
	s_waitcnt lgkmcnt(7)
	v_mov_b32_e32 v109, v86
	s_waitcnt lgkmcnt(3)
	v_mov_b32_e32 v108, v94
	v_mov_b32_e32 v86, v95
	s_waitcnt lgkmcnt(2)
	v_mov_b32_e32 v94, v96
	v_mov_b32_e32 v95, v88
	v_mov_b32_e32 v88, v97
	s_waitcnt lgkmcnt(1)
	v_mov_b32_e32 v96, v100
	v_mov_b32_e32 v97, v90
	v_mov_b32_e32 v90, v101
	s_waitcnt lgkmcnt(0)
	v_mov_b32_e32 v100, v102
	v_mov_b32_e32 v101, v92
	v_mov_b32_e32 v92, v103
	v_pk_add_f32 v[102:103], v[108:109], 0 op_sel_hi:[1,0]
	v_lshlrev_b64 v[84:85], 11, v[84:85]
	v_pk_add_f32 v[86:87], v[102:103], v[86:87]
	s_mov_b32 s37, s43
	v_pk_add_f32 v[86:87], v[86:87], v[94:95]
	v_ashrrev_i32_e32 v105, 31, v104
	v_pk_add_f32 v[86:87], v[86:87], v[88:89]
	v_lshl_add_u64 v[84:85], s[38:39], 0, v[84:85]
	v_pk_add_f32 v[86:87], v[86:87], v[96:97]
	s_lshl_b32 s36, s36, 1
	v_pk_add_f32 v[86:87], v[86:87], v[90:91]
	s_mov_b32 s65, s43
	v_pk_add_f32 v[86:87], v[86:87], v[100:101]
	v_lshlrev_b64 v[106:107], 13, v[104:105]
	v_pk_add_f32 v[86:87], v[86:87], v[92:93]
	s_lshl_b32 s64, s51, 1
	v_pk_fma_f32 v[86:87], v[86:87], s[52:53], v[32:33] op_sel_hi:[1,0,0]
	v_lshl_add_u64 v[84:85], v[84:85], 0, s[36:37]
	v_mul_f32_e32 v27, 0x4b800000, v87
	v_cmp_gt_f32_e64 s[34:35], s69, v87
	v_lshlrev_b32_e32 v28, 1, v98
	v_mov_b32_e32 v29, v23
	v_cndmask_b32_e64 v27, v87, v27, s[34:35]
	v_rsq_f32_e32 v27, v27
	v_lshl_add_u64 v[106:107], s[44:45], 0, v[106:107]
	v_lshl_add_u64 v[84:85], v[84:85], 0, s[64:65]
	v_lshl_add_u64 v[106:107], v[106:107], 0, s[42:43]
	v_lshl_add_u64 v[84:85], v[84:85], 0, v[28:29]
	v_or_b32_e32 v94, s73, v70
	v_ashrrev_i32_e32 v95, 31, v94
	v_lshlrev_b64 v[96:97], 13, v[94:95]
	v_lshl_add_u64 v[96:97], s[44:45], 0, v[96:97]
	v_lshl_add_u64 v[96:97], v[96:97], 0, s[42:43]
	s_add_i32 s40, s40, s56
	v_lshl_add_u64 v[24:25], v[24:25], 0, s[46:47]
	s_waitcnt vmcnt(4)
	v_mul_f32_e32 v79, 0xbfb8aa3b, v80
	v_mul_f32_e32 v87, 0xbfb8aa3b, v81
	v_mul_f32_e32 v88, 0xbfb8aa3b, v82
	v_mul_f32_e32 v89, 0xbfb8aa3b, v83
	v_exp_f32_e32 v79, v79
	v_exp_f32_e32 v87, v87
	v_exp_f32_e32 v88, v88
	v_exp_f32_e32 v89, v89
	v_add_f32_e32 v79, 1.0, v79
	v_add_f32_e32 v87, 1.0, v87
	v_add_f32_e32 v90, 1.0, v88
	v_add_f32_e32 v91, 1.0, v89
	v_rcp_f32_e32 v88, v79
	v_rcp_f32_e32 v89, v87
	v_rcp_f32_e32 v90, v90
	v_rcp_f32_e32 v91, v91
	v_mul_f32_e32 v79, 0x45800000, v27
	v_pk_mul_f32 v[80:81], v[80:81], v[88:89]
	v_cndmask_b32_e64 v92, v27, v79, s[34:35]
	v_pk_mul_f32 v[82:83], v[82:83], v[90:91]
	v_pk_mul_f32 v[18:19], v[18:19], v[80:81]
	v_pk_mul_f32 v[20:21], v[20:21], v[82:83]
	v_pk_mul_f32 v[18:19], v[92:93], v[18:19] op_sel_hi:[0,1]
	v_pk_mul_f32 v[20:21], v[92:93], v[20:21] op_sel_hi:[0,1]
	s_waitcnt vmcnt(0)
	v_pk_mul_f32 v[18:19], v[10:11], v[18:19]
	v_pk_mul_f32 v[20:21], v[12:13], v[20:21]
	v_cvt_pk_bf16_f32 v18, v18, v19
	v_cvt_pk_bf16_f32 v19, v20, v21
	global_store_dwordx2 v[84:85], v[18:19], off offset:1024
	v_lshl_add_u64 v[18:19], v[106:107], 0, s[66:67]
	v_lshl_add_u64 v[18:19], v[18:19], 0, v[30:31]
	v_add_co_u32_e64 v18, s[34:35], s72, v18
	v_or_b32_e32 v80, s73, v68
	s_nop 0
	v_addc_co_u32_e64 v19, s[34:35], 0, v19, s[34:35]
	v_mov_b64_e32 v[18:19], v[208:209]
	v_mov_b64_e32 v[20:21], v[210:211]
	v_ashrrev_i32_e32 v81, 31, v80
	v_lshlrev_b64 v[84:85], 13, v[80:81]
	v_lshl_add_u64 v[84:85], s[44:45], 0, v[84:85]
	v_lshl_add_u64 v[84:85], v[84:85], 0, s[42:43]
	v_lshl_add_u64 v[84:85], v[84:85], 0, s[66:67]
	v_lshl_add_u64 v[84:85], v[84:85], 0, v[30:31]
	v_add_co_u32_e64 v84, s[34:35], s72, v84
	v_mul_f32_e32 v27, 0x4b800000, v86
	s_nop 0
	v_addc_co_u32_e64 v85, s[34:35], 0, v85, s[34:35]
	v_cmp_gt_f32_e64 s[34:35], s69, v86
	v_lshlrev_b64 v[82:83], 11, v[104:105]
	v_lshl_add_u64 v[82:83], s[38:39], 0, v[82:83]
	v_cndmask_b32_e64 v27, v86, v27, s[34:35]
	v_rsq_f32_e32 v27, v27
	v_lshl_add_u64 v[82:83], v[82:83], 0, s[36:37]
	v_lshl_add_u64 v[82:83], v[82:83], 0, s[64:65]
	v_lshl_add_u64 v[82:83], v[82:83], 0, v[28:29]
	v_lshlrev_b64 v[80:81], 11, v[80:81]
	v_lshl_add_u64 v[80:81], s[38:39], 0, v[80:81]
	v_mul_f32_e32 v79, 0xbfb8aa3b, v18
	v_mul_f32_e32 v86, 0xbfb8aa3b, v19
	v_mul_f32_e32 v87, 0xbfb8aa3b, v20
	v_mul_f32_e32 v88, 0xbfb8aa3b, v21
	v_exp_f32_e32 v79, v79
	v_exp_f32_e32 v86, v86
	v_exp_f32_e32 v87, v87
	v_exp_f32_e32 v88, v88
	v_add_f32_e32 v79, 1.0, v79
	v_add_f32_e32 v89, 1.0, v86
	v_add_f32_e32 v90, 1.0, v87
	v_add_f32_e32 v91, 1.0, v88
	v_rcp_f32_e32 v86, v79
	v_rcp_f32_e32 v87, v89
	v_rcp_f32_e32 v88, v90
	v_rcp_f32_e32 v89, v91
	v_mul_f32_e32 v79, 0x45800000, v27
	v_pk_mul_f32 v[18:19], v[18:19], v[86:87]
	v_cndmask_b32_e64 v90, v27, v79, s[34:35]
	v_pk_mul_f32 v[20:21], v[20:21], v[88:89]
	v_pk_mul_f32 v[14:15], v[14:15], v[18:19]
	v_pk_mul_f32 v[16:17], v[16:17], v[20:21]
	v_pk_mul_f32 v[14:15], v[90:91], v[14:15] op_sel_hi:[0,1]
	v_pk_mul_f32 v[16:17], v[90:91], v[16:17] op_sel_hi:[0,1]
	v_pk_mul_f32 v[14:15], v[10:11], v[14:15]
	v_pk_mul_f32 v[16:17], v[12:13], v[16:17]
	v_cvt_pk_bf16_f32 v14, v14, v15
	v_cvt_pk_bf16_f32 v15, v16, v17
	global_store_dwordx2 v[82:83], v[14:15], off offset:1024
	v_mov_b64_e32 v[14:15], v[212:213]
	v_mov_b64_e32 v[16:17], v[214:215]
	ds_read2st64_b32 v[18:19], v69 offset1:1
	ds_read2st64_b32 v[20:21], v69 offset0:2 offset1:3
	ds_read2st64_b32 v[82:83], v69 offset0:4 offset1:5
	ds_read2st64_b32 v[84:85], v69 offset0:6 offset1:7
	ds_read2st64_b32 v[86:87], v71 offset1:1
	ds_read2st64_b32 v[88:89], v71 offset0:2 offset1:3
	ds_read2st64_b32 v[90:91], v71 offset0:4 offset1:5
	ds_read2st64_b32 v[92:93], v71 offset0:6 offset1:7
	s_waitcnt lgkmcnt(7)
	v_mov_b32_e32 v101, v18
	s_waitcnt lgkmcnt(3)
	v_mov_b32_e32 v100, v86
	v_mov_b32_e32 v18, v87
	s_waitcnt lgkmcnt(2)
	v_mov_b32_e32 v86, v88
	v_mov_b32_e32 v87, v20
	v_mov_b32_e32 v20, v89
	s_waitcnt lgkmcnt(1)
	v_mov_b32_e32 v88, v90
	v_mov_b32_e32 v89, v82
	v_mov_b32_e32 v82, v91
	s_waitcnt lgkmcnt(0)
	v_mov_b32_e32 v90, v92
	v_mov_b32_e32 v91, v84
	v_mov_b32_e32 v84, v93
	v_pk_add_f32 v[92:93], v[100:101], 0 op_sel_hi:[1,0]
	v_mul_f32_e32 v79, 0xbfb8aa3b, v17
	v_pk_add_f32 v[18:19], v[92:93], v[18:19]
	v_exp_f32_e32 v79, v79
	v_pk_add_f32 v[18:19], v[18:19], v[86:87]
	v_lshl_add_u64 v[86:87], v[96:97], 0, s[66:67]
	v_pk_add_f32 v[18:19], v[18:19], v[20:21]
	v_lshl_add_u64 v[20:21], v[86:87], 0, v[30:31]
	v_pk_add_f32 v[18:19], v[18:19], v[88:89]
	v_add_co_u32_e64 v20, s[34:35], s72, v20
	v_pk_add_f32 v[18:19], v[18:19], v[82:83]
	s_nop 0
	v_addc_co_u32_e64 v21, s[34:35], 0, v21, s[34:35]
	v_pk_add_f32 v[18:19], v[18:19], v[90:91]
	v_lshl_add_u64 v[30:31], v[80:81], 0, s[36:37]
	v_pk_add_f32 v[18:19], v[18:19], v[84:85]
	v_add_f32_e32 v79, 1.0, v79
	v_pk_fma_f32 v[18:19], v[18:19], s[52:53], v[32:33] op_sel_hi:[1,0,0]
	v_mul_f32_e32 v32, 0xbfb8aa3b, v15
	v_mul_f32_e32 v27, 0x4b800000, v19
	v_cmp_gt_f32_e64 s[34:35], s69, v19
	v_mul_f32_e32 v33, 0xbfb8aa3b, v16
	v_exp_f32_e32 v32, v32
	v_cndmask_b32_e64 v19, v19, v27, s[34:35]
	v_mul_f32_e32 v27, 0xbfb8aa3b, v14
	v_exp_f32_e32 v27, v27
	v_exp_f32_e32 v33, v33
	v_add_f32_e32 v80, 1.0, v32
	v_rsq_f32_e32 v19, v19
	v_add_f32_e32 v27, 1.0, v27
	v_add_f32_e32 v81, 1.0, v33
	v_rcp_f32_e32 v32, v27
	v_rcp_f32_e32 v33, v80
	v_rcp_f32_e32 v80, v81
	v_rcp_f32_e32 v81, v79
	v_mul_f32_e32 v27, 0x45800000, v19
	v_pk_mul_f32 v[14:15], v[14:15], v[32:33]
	v_cndmask_b32_e64 v82, v19, v27, s[34:35]
	v_pk_mul_f32 v[16:17], v[16:17], v[80:81]
	v_pk_mul_f32 v[6:7], v[6:7], v[14:15]
	v_pk_mul_f32 v[8:9], v[8:9], v[16:17]
	v_pk_mul_f32 v[6:7], v[82:83], v[6:7] op_sel_hi:[0,1]
	v_pk_mul_f32 v[8:9], v[82:83], v[8:9] op_sel_hi:[0,1]
	v_lshl_add_u64 v[30:31], v[30:31], 0, s[64:65]
	v_pk_mul_f32 v[6:7], v[10:11], v[6:7]
	v_pk_mul_f32 v[8:9], v[12:13], v[8:9]
	v_lshl_add_u64 v[30:31], v[30:31], 0, v[28:29]
	v_cvt_pk_bf16_f32 v6, v6, v7
	v_cvt_pk_bf16_f32 v7, v8, v9
	global_store_dwordx2 v[30:31], v[6:7], off offset:1024
	v_mov_b64_e32 v[6:7], v[216:217]
	v_mov_b64_e32 v[8:9], v[218:219]
	v_mul_f32_e32 v16, 0x4b800000, v18
	v_cmp_gt_f32_e64 s[34:35], s69, v18
	v_lshlrev_b64 v[14:15], 11, v[94:95]
	v_lshl_add_u64 v[14:15], s[38:39], 0, v[14:15]
	v_cndmask_b32_e64 v16, v18, v16, s[34:35]
	v_rsq_f32_e32 v20, v16
	v_lshl_add_u64 v[14:15], v[14:15], 0, s[36:37]
	s_add_i32 s53, s53, s55
	v_lshl_add_u64 v[14:15], v[14:15], 0, s[64:65]
	v_mul_f32_e32 v21, 0x45800000, v20
	v_cndmask_b32_e64 v20, v20, v21, s[34:35]
	s_cmpk_lt_i32 s40, 0x180
	v_lshl_add_u64 v[14:15], v[14:15], 0, v[28:29]
	v_mul_f32_e32 v16, 0xbfb8aa3b, v6
	v_mul_f32_e32 v17, 0xbfb8aa3b, v7
	v_mul_f32_e32 v18, 0xbfb8aa3b, v8
	v_mul_f32_e32 v19, 0xbfb8aa3b, v9
	v_exp_f32_e32 v16, v16
	v_exp_f32_e32 v17, v17
	v_exp_f32_e32 v18, v18
	v_exp_f32_e32 v19, v19
	v_add_f32_e32 v16, 1.0, v16
	v_add_f32_e32 v17, 1.0, v17
	v_add_f32_e32 v18, 1.0, v18
	v_add_f32_e32 v19, 1.0, v19
	v_rcp_f32_e32 v16, v16
	v_rcp_f32_e32 v17, v17
	v_rcp_f32_e32 v18, v18
	v_rcp_f32_e32 v19, v19
	v_pk_mul_f32 v[6:7], v[6:7], v[16:17]
	s_nop 0
	v_pk_mul_f32 v[2:3], v[2:3], v[6:7]
	v_pk_mul_f32 v[8:9], v[8:9], v[18:19]
	v_pk_mul_f32 v[2:3], v[20:21], v[2:3] op_sel_hi:[0,1]
	v_pk_mul_f32 v[4:5], v[4:5], v[8:9]
	v_pk_mul_f32 v[2:3], v[10:11], v[2:3]
	v_pk_mul_f32 v[4:5], v[20:21], v[4:5] op_sel_hi:[0,1]
	v_pk_mul_f32 v[4:5], v[12:13], v[4:5]
	v_cvt_pk_bf16_f32 v2, v2, v3
	v_cvt_pk_bf16_f32 v3, v4, v5
	global_store_dwordx2 v[14:15], v[2:3], off offset:1024
	s_barrier
	s_cbranch_scc0 .LBB0_1106
